# RWKV units: loop-edge edit - chain waves get a private loop latch (counter, barrier, exit test) that skips the preppers' vmcnt waits and register-rotation copies on the way back to stage H
# baseline (speedup 1.0000x reference)
.LBB0_368:
	v_mov_b64_e32 v[24:25], v[52:53]
	v_mov_b64_e32 v[28:29], v[44:45]
	v_mov_b64_e32 v[32:33], v[48:49]
	v_mov_b64_e32 v[20:21], v[40:41]
	v_mov_b64_e32 v[146:147], v[116:117]
	v_mov_b64_e32 v[152:153], v[112:113]
	v_mov_b64_e32 v[144:145], v[118:119]
	v_mov_b64_e32 v[150:151], v[120:121]
	v_mov_b64_e32 v[0:1], v[114:115]
	v_mov_b64_e32 v[148:149], v[110:111]
	v_mov_b64_e32 v[26:27], v[54:55]
	v_mov_b64_e32 v[30:31], v[46:47]
	v_mov_b64_e32 v[34:35], v[50:51]
	v_mov_b64_e32 v[22:23], v[42:43]
	s_mov_b32 s26, s27
	s_add_i32 s77, s77, 32
	s_sub_i32 s76, s76, 32
	s_cmpk_eq_i32 s77, 0x140
	s_waitcnt lgkmcnt(0)
	s_barrier
	s_cbranch_scc1 .LBB0_384
	s_andn2_b64 vcc, exec, s[24:25]
	s_mov_b64 s[28:29], -1
	s_branch .LBB0_356

.LBB0_453:
	v_mov_b64_e32 v[16:17], v[52:53]
	v_mov_b64_e32 v[12:13], v[44:45]
	v_mov_b64_e32 v[8:9], v[48:49]
	v_mov_b64_e32 v[4:5], v[40:41]
	v_mov_b64_e32 v[142:143], v[114:115]
	v_mov_b64_e32 v[148:149], v[110:111]
	v_mov_b64_e32 v[140:141], v[116:117]
	v_mov_b64_e32 v[146:147], v[118:119]
	v_mov_b64_e32 v[0:1], v[112:113]
	v_mov_b64_e32 v[144:145], v[108:109]
	v_mov_b64_e32 v[18:19], v[54:55]
	v_mov_b64_e32 v[14:15], v[46:47]
	v_mov_b64_e32 v[10:11], v[50:51]
	v_mov_b64_e32 v[6:7], v[42:43]
	s_mov_b32 s76, s28
	s_add_i32 s71, s71, 32
	s_sub_i32 s70, s70, 32
	s_cmpk_lg_i32 s71, 0x840
	s_waitcnt lgkmcnt(0)
	s_barrier
	s_cbranch_scc0 .LBB0_481
	s_branch .LBB0_455

.LBB0_1026:
	v_mov_b64_e32 v[16:17], v[52:53]
	v_mov_b64_e32 v[12:13], v[44:45]
	v_mov_b64_e32 v[8:9], v[48:49]
	v_mov_b64_e32 v[4:5], v[40:41]
	v_mov_b64_e32 v[142:143], v[114:115]
	v_mov_b64_e32 v[148:149], v[110:111]
	v_mov_b64_e32 v[140:141], v[116:117]
	v_mov_b64_e32 v[146:147], v[118:119]
	v_mov_b64_e32 v[0:1], v[112:113]
	v_mov_b64_e32 v[144:145], v[108:109]
	v_mov_b64_e32 v[18:19], v[54:55]
	v_mov_b64_e32 v[14:15], v[46:47]
	v_mov_b64_e32 v[10:11], v[50:51]
	v_mov_b64_e32 v[6:7], v[42:43]
	s_mov_b32 s76, s28
	s_add_i32 s69, s69, 32
	s_sub_i32 s68, s68, 32
	s_cmpk_lg_i32 s69, 0x840
	s_waitcnt lgkmcnt(0)
	s_barrier
	s_cbranch_scc0 .LBB0_1054
	s_branch .LBB0_1028
